# nt hint on the f32 input row loads of the layer-0 operand conversion
# speedup vs baseline: 1.0138x; 1.0072x over previous
.LBB0_1443:
	s_lshr_b32 s18, s90, 5
	s_load_dwordx2 s[10:11], s[0:1], 0x38
	s_load_dwordx2 s[16:17], s[0:1], 0x98
	s_ashr_i32 s15, s2, 11
	s_add_i32 s18, s18, 32
	s_and_b64 s[8:9], s[8:9], exec
	s_cselect_b32 s8, s15, s18
	s_mul_hi_i32 s9, s8, 0x3000
	s_mulk_i32 s8, 0x3000
	v_lshlrev_b32_e32 v0, 2, v48
	s_waitcnt lgkmcnt(0)
	s_add_u32 s8, s16, s8
	global_load_dwordx4 v[74:77], v0, s[4:5]
	global_load_dwordx4 v[78:81], v0, s[4:5] offset:1024
	s_addc_u32 s9, s17, s9
	s_add_u32 s8, s8, 0x201000
	s_addc_u32 s9, s9, 0
	global_load_dwordx4 v[50:53], v0, s[8:9]
	global_load_dwordx4 v[54:57], v71, s[8:9]
	global_load_dwordx4 v[58:61], v72, s[8:9]
	global_load_dwordx4 v[62:65], v73, s[8:9]
	global_load_dwordx4 v[82:85], v0, s[10:11]
	global_load_dwordx4 v[86:89], v0, s[10:11] offset:1024
	global_load_dwordx4 v[90:93], v0, s[10:11] offset:2048
	global_load_dwordx4 v[98:101], v0, s[10:11] offset:3072
	global_load_dwordx4 v[102:105], v0, s[4:5] offset:2048
	global_load_dwordx4 v[106:109], v0, s[4:5] offset:3072
	v_mov_b32_e32 v1, v97
	v_lshl_add_u64 v[2:3], s[4:5], 0, v[0:1]
	v_add_co_u32_e32 v0, vcc, s53, v2
	s_lshl_b64 s[4:5], s[2:3], 11
	s_nop 0
	v_addc_co_u32_e32 v1, vcc, 0, v3, vcc
	v_add_co_u32_e32 v4, vcc, s58, v2
	s_waitcnt vmcnt(9)
	v_pk_add_f32 v[52:53], v[52:53], 1.0 op_sel_hi:[1,0]
	v_addc_co_u32_e32 v5, vcc, 0, v3, vcc
	v_add_co_u32_e32 v2, vcc, s64, v2
	v_pk_add_f32 v[50:51], v[50:51], 1.0 op_sel_hi:[1,0]
	s_nop 0
	v_addc_co_u32_e32 v3, vcc, 0, v3, vcc
	global_load_dwordx4 v[44:47], v[4:5], off offset:-4096 nt
	global_load_dwordx4 v[40:43], v[0:1], off offset:1024 nt
	global_load_dwordx4 v[36:39], v[0:1], off offset:2048 nt
	global_load_dwordx4 v[28:31], v[4:5], off nt
	global_load_dwordx4 v[24:27], v[4:5], off offset:1024 nt
	global_load_dwordx4 v[20:23], v[4:5], off offset:2048 nt
	global_load_dwordx4 v[16:19], v[4:5], off offset:3072 nt
	global_load_dwordx4 v[32:35], v[0:1], off offset:3072 nt
	global_load_dwordx4 v[12:15], v[2:3], off nt
	global_load_dwordx4 v[8:11], v[2:3], off offset:1024 nt
	s_nop 0
	global_load_dwordx4 v[4:7], v[2:3], off offset:2048 nt
	s_nop 0
	global_load_dwordx4 v[0:3], v[2:3], off offset:3072 nt
	s_load_dwordx2 s[8:9], s[0:1], 0x98
	v_mul_f32_e32 v110, v75, v75
	v_mul_f32_e32 v111, v77, v77
	s_waitcnt vmcnt(18)
	v_pk_add_f32 v[114:115], v[64:65], 1.0 op_sel_hi:[1,0]
	v_pk_add_f32 v[116:117], v[62:63], 1.0 op_sel_hi:[1,0]
	s_waitcnt lgkmcnt(0)
	s_add_u32 s8, s8, s4
	s_addc_u32 s9, s9, s5
	v_lshl_add_u64 v[94:95], s[8:9], 0, v[96:97]
	s_waitcnt vmcnt(17)
	v_pk_mul_f32 v[62:63], v[84:85], v[52:53]
	v_pk_mul_f32 v[64:65], v[82:83], v[50:51]
	v_add_co_u32_e32 v94, vcc, s75, v94
	v_fmac_f32_e32 v110, v74, v74
	v_fmac_f32_e32 v111, v76, v76
	v_pk_mul_f32 v[76:77], v[62:63], v[76:77]
	v_pk_mul_f32 v[74:75], v[64:65], v[74:75]
	v_addc_co_u32_e32 v95, vcc, 0, v95, vcc
	v_cvt_pk_bf16_f32 v74, v74, v75
	v_cvt_pk_bf16_f32 v75, v76, v77
	global_store_dwordx2 v[94:95], v[74:75], off
	s_load_dwordx2 s[8:9], s[0:1], 0x98
	v_mul_f32_e32 v112, v79, v79
	v_mul_f32_e32 v113, v81, v81
	v_fmac_f32_e32 v112, v78, v78
	v_fmac_f32_e32 v113, v80, v80
	v_add_f32_e32 v110, v110, v111
	v_add_f32_e32 v111, v112, v113
	v_pk_add_f32 v[56:57], v[56:57], 1.0 op_sel_hi:[1,0]
	v_pk_add_f32 v[54:55], v[54:55], 1.0 op_sel_hi:[1,0]
	v_add_f32_e32 v118, v110, v111
	v_pk_add_f32 v[110:111], v[60:61], 1.0 op_sel_hi:[1,0]
	v_pk_add_f32 v[112:113], v[58:59], 1.0 op_sel_hi:[1,0]
	s_waitcnt vmcnt(17)
	v_pk_mul_f32 v[58:59], v[88:89], v[56:57]
	v_pk_mul_f32 v[60:61], v[86:87], v[54:55]
	s_waitcnt lgkmcnt(0)
	s_add_u32 s8, s8, s4
	v_pk_mul_f32 v[74:75], v[58:59], v[80:81]
	v_pk_mul_f32 v[76:77], v[60:61], v[78:79]
	s_addc_u32 s9, s9, s5
	v_cvt_pk_bf16_f32 v76, v76, v77
	v_cvt_pk_bf16_f32 v77, v74, v75
	v_lshl_add_u64 v[74:75], s[8:9], 0, v[96:97]
	v_add_co_u32_e32 v74, vcc, s75, v74
	s_waitcnt vmcnt(16)
	v_pk_mul_f32 v[54:55], v[92:93], v[110:111]
	v_addc_co_u32_e32 v75, vcc, 0, v75, vcc
	global_store_dwordx2 v[74:75], v[76:77], off offset:512
	s_waitcnt vmcnt(15)
	v_mul_f32_e32 v74, v103, v103
	v_mul_f32_e32 v75, v105, v105
	v_fmac_f32_e32 v74, v102, v102
	v_fmac_f32_e32 v75, v104, v104
	v_add_f32_e32 v74, v74, v75
	s_waitcnt vmcnt(14)
	v_mul_f32_e32 v75, v107, v107
	v_mul_f32_e32 v76, v109, v109
	v_fmac_f32_e32 v75, v106, v106
	v_fmac_f32_e32 v76, v108, v108
	v_add_f32_e32 v74, v118, v74
	v_add_f32_e32 v75, v75, v76
	v_add_f32_e32 v78, v74, v75
	ds_bpermute_b32 v79, v49, v78
	s_load_dwordx2 s[8:9], s[0:1], 0x98
	v_pk_mul_f32 v[56:57], v[90:91], v[112:113]
	v_pk_mul_f32 v[74:75], v[54:55], v[104:105]
	v_pk_mul_f32 v[76:77], v[56:57], v[102:103]
	s_waitcnt lgkmcnt(0)
	v_add_f32_e32 v78, v78, v79
	ds_bpermute_b32 v79, v66, v78
	s_add_u32 s8, s8, s4
	s_addc_u32 s9, s9, s5
	v_cvt_pk_bf16_f32 v76, v76, v77
	v_cvt_pk_bf16_f32 v77, v74, v75
	s_waitcnt lgkmcnt(0)
	v_add_f32_e32 v78, v78, v79
	ds_bpermute_b32 v79, v67, v78
	v_lshl_add_u64 v[74:75], s[8:9], 0, v[96:97]
	v_add_co_u32_e32 v74, vcc, s75, v74
	v_pk_mul_f32 v[50:51], v[100:101], v[114:115]
	s_waitcnt lgkmcnt(0)
	v_add_f32_e32 v78, v78, v79
	ds_bpermute_b32 v79, v68, v78
	v_addc_co_u32_e32 v75, vcc, 0, v75, vcc
	global_store_dwordx2 v[74:75], v[76:77], off offset:1024
	s_load_dwordx2 s[8:9], s[0:1], 0x98
	s_waitcnt lgkmcnt(0)
	v_add_f32_e32 v80, v78, v79
	ds_bpermute_b32 v81, v69, v80
	v_pk_mul_f32 v[52:53], v[98:99], v[116:117]
	v_pk_mul_f32 v[74:75], v[50:51], v[108:109]
	v_pk_mul_f32 v[76:77], v[52:53], v[106:107]
	s_add_u32 s4, s8, s4
	v_cvt_pk_bf16_f32 v76, v76, v77
	v_cvt_pk_bf16_f32 v77, v74, v75
	s_waitcnt lgkmcnt(0)
	v_add_f32_e32 v74, v80, v81
	ds_bpermute_b32 v75, v70, v74
	s_addc_u32 s5, s9, s5
	v_lshl_add_u64 v[78:79], s[4:5], 0, v[96:97]
	v_add_co_u32_e32 v78, vcc, s75, v78
	s_nop 1
	v_addc_co_u32_e32 v79, vcc, 0, v79, vcc
	global_store_dwordx2 v[78:79], v[76:77], off offset:1536
	s_and_saveexec_b64 s[4:5], s[6:7]
	s_cbranch_execz .LBB0_1445
	s_load_dwordx2 s[8:9], s[0:1], 0x98
	s_lshl_b64 s[10:11], s[2:3], 4
	s_waitcnt lgkmcnt(0)
	v_add_f32_e32 v74, v74, v75
	v_mov_b32_e32 v75, v97
	v_mov_b32_e32 v76, v97
	s_add_u32 s8, s8, s10
	s_addc_u32 s9, s9, s11
	v_mov_b32_e32 v77, v97
	global_store_dwordx4 v213, v[74:77], s[8:9]
